# GEMM phases: priority toggling inverted - raised during the LDS/global load sections, lowered during MFMA clusters
# baseline (speedup 1.0000x reference)
.LBB0_102:
	ds_read_b128 v[156:159], v152
	ds_read_b128 v[160:163], v152 offset:1024
	ds_read_b128 v[164:167], v152 offset:2048
	ds_read_b128 v[168:171], v152 offset:3072
	s_add_i32 vcc_hi, s80, 2
	s_add_u32 s82, s78, 0x80
	s_addc_u32 s81, s79, 0
	s_cmp_eq_u32 s92, s80
	s_cselect_b32 s80, s0, s82
	s_cselect_b32 s81, s1, s81
	s_cselect_b32 s83, s9, vcc_lo
	s_cselect_b32 s82, s8, s73
	v_lshl_add_u64 v[148:149], s[78:79], 0, v[140:141]
	s_add_i32 m0, s84, 0xc000
	ds_read_b128 v[172:175], v153
	ds_read_b128 v[176:179], v153 offset:1024
	ds_read_b128 v[182:185], v153 offset:2048
	ds_read_b128 v[186:189], v153 offset:3072
	ds_read_b128 v[190:193], v153 offset:4096
	ds_read_b128 v[194:197], v153 offset:5120
	ds_read_b128 v[198:201], v153 offset:6144
	ds_read_b128 v[202:205], v153 offset:7168
	global_load_lds_dwordx4 v[148:149], off
	v_lshl_add_u64 v[148:149], s[78:79], 0, v[142:143]
	s_add_i32 m0, s84, 0xe000
	s_nop 0
	global_load_lds_dwordx4 v[148:149], off
	s_waitcnt lgkmcnt(8)
	s_barrier
	s_waitcnt lgkmcnt(0)
	s_setprio 0
	s_waitcnt lgkmcnt(0)
	v_mfma_f32_16x16x32_bf16 v[126:129], v[156:159], v[172:175], v[126:129]
	v_mfma_f32_16x16x32_bf16 v[122:125], v[164:167], v[172:175], v[122:125]
	v_mfma_f32_16x16x32_bf16 v[118:121], v[156:159], v[182:185], v[118:121]
	v_mfma_f32_16x16x32_bf16 v[114:117], v[164:167], v[182:185], v[114:117]
	v_mfma_f32_16x16x32_bf16 v[94:97], v[156:159], v[190:193], v[94:97]
	v_mfma_f32_16x16x32_bf16 v[90:93], v[164:167], v[190:193], v[90:93]
	v_mfma_f32_16x16x32_bf16 v[86:89], v[156:159], v[198:201], v[86:89]
	v_mfma_f32_16x16x32_bf16 v[82:85], v[164:167], v[198:201], v[82:85]
	v_mfma_f32_16x16x32_bf16 v[126:129], v[160:163], v[176:179], v[126:129]
	v_mfma_f32_16x16x32_bf16 v[122:125], v[168:171], v[176:179], v[122:125]
	v_mfma_f32_16x16x32_bf16 v[118:121], v[160:163], v[186:189], v[118:121]
	v_mfma_f32_16x16x32_bf16 v[114:117], v[168:171], v[186:189], v[114:117]
	v_mfma_f32_16x16x32_bf16 v[94:97], v[160:163], v[194:197], v[94:97]
	v_mfma_f32_16x16x32_bf16 v[90:93], v[168:171], v[194:197], v[90:93]
	v_mfma_f32_16x16x32_bf16 v[86:89], v[160:163], v[202:205], v[86:89]
	v_mfma_f32_16x16x32_bf16 v[82:85], v[168:171], v[202:205], v[82:85]
	s_setprio 1
	s_barrier
	s_add_i32 s74, s16, s71
	v_lshl_add_u64 v[148:149], s[82:83], 0, v[132:133]
	s_mov_b32 m0, s74
	ds_read_b128 v[206:209], v154
	ds_read_b128 v[210:213], v154 offset:1024
	ds_read_b128 v[214:217], v154 offset:2048
	ds_read_b128 v[218:221], v154 offset:3072
	global_load_lds_dwordx4 v[148:149], off
	v_lshl_add_u64 v[222:223], s[82:83], 0, v[136:137]
	s_add_i32 m0, s74, 0x2000
	s_nop 0
	global_load_lds_dwordx4 v[222:223], off
	s_barrier
	s_waitcnt lgkmcnt(0)
	s_setprio 0
	s_waitcnt lgkmcnt(0)
	v_mfma_f32_16x16x32_bf16 v[110:113], v[206:209], v[172:175], v[110:113]
	v_mfma_f32_16x16x32_bf16 v[106:109], v[214:217], v[172:175], v[106:109]
	v_mfma_f32_16x16x32_bf16 v[102:105], v[206:209], v[182:185], v[102:105]
	v_mfma_f32_16x16x32_bf16 v[98:101], v[214:217], v[182:185], v[98:101]
	v_mfma_f32_16x16x32_bf16 v[78:81], v[206:209], v[190:193], v[78:81]
	v_mfma_f32_16x16x32_bf16 v[74:77], v[214:217], v[190:193], v[74:77]
	v_mfma_f32_16x16x32_bf16 v[70:73], v[206:209], v[198:201], v[70:73]
	v_mfma_f32_16x16x32_bf16 v[66:69], v[214:217], v[198:201], v[66:69]
	v_mfma_f32_16x16x32_bf16 v[110:113], v[210:213], v[176:179], v[110:113]
	v_mfma_f32_16x16x32_bf16 v[106:109], v[218:221], v[176:179], v[106:109]
	v_mfma_f32_16x16x32_bf16 v[102:105], v[210:213], v[186:189], v[102:105]
	v_mfma_f32_16x16x32_bf16 v[98:101], v[218:221], v[186:189], v[98:101]
	v_mfma_f32_16x16x32_bf16 v[78:81], v[210:213], v[194:197], v[78:81]
	v_mfma_f32_16x16x32_bf16 v[74:77], v[218:221], v[194:197], v[74:77]
	v_mfma_f32_16x16x32_bf16 v[70:73], v[210:213], v[202:205], v[70:73]
	v_mfma_f32_16x16x32_bf16 v[66:69], v[218:221], v[202:205], v[66:69]
	s_setprio 1
	s_mov_b32 m0, s84
	v_lshl_add_u64 v[224:225], s[80:81], 0, v[130:131]
	s_barrier
	ds_read_b128 v[172:175], v153 offset:16384
	ds_read_b128 v[176:179], v153 offset:17408
	ds_read_b128 v[182:185], v153 offset:18432
	ds_read_b128 v[186:189], v153 offset:19456
	ds_read_b128 v[190:193], v153 offset:20480
	ds_read_b128 v[194:197], v153 offset:21504
	ds_read_b128 v[198:201], v153 offset:22528
	ds_read_b128 v[202:205], v153 offset:23552
	global_load_lds_dwordx4 v[224:225], off
	v_lshl_add_u64 v[226:227], s[80:81], 0, v[134:135]
	s_mov_b32 m0, s85
	s_nop 0
	global_load_lds_dwordx4 v[226:227], off
	s_barrier
	s_waitcnt lgkmcnt(0)
	s_setprio 0
	s_waitcnt lgkmcnt(0)
	v_mfma_f32_16x16x32_bf16 v[62:65], v[156:159], v[172:175], v[62:65]
	v_mfma_f32_16x16x32_bf16 v[58:61], v[164:167], v[172:175], v[58:61]
	v_mfma_f32_16x16x32_bf16 v[54:57], v[156:159], v[182:185], v[54:57]
	v_mfma_f32_16x16x32_bf16 v[50:53], v[164:167], v[182:185], v[50:53]
	v_mfma_f32_16x16x32_bf16 v[30:33], v[156:159], v[190:193], v[30:33]
	v_mfma_f32_16x16x32_bf16 v[26:29], v[164:167], v[190:193], v[26:29]
	v_mfma_f32_16x16x32_bf16 v[22:25], v[156:159], v[198:201], v[22:25]
	v_mfma_f32_16x16x32_bf16 v[18:21], v[164:167], v[198:201], v[18:21]
	v_mfma_f32_16x16x32_bf16 v[62:65], v[160:163], v[176:179], v[62:65]
	v_mfma_f32_16x16x32_bf16 v[58:61], v[168:171], v[176:179], v[58:61]
	v_mfma_f32_16x16x32_bf16 v[54:57], v[160:163], v[186:189], v[54:57]
	v_mfma_f32_16x16x32_bf16 v[50:53], v[168:171], v[186:189], v[50:53]
	v_mfma_f32_16x16x32_bf16 v[30:33], v[160:163], v[194:197], v[30:33]
	v_mfma_f32_16x16x32_bf16 v[26:29], v[168:171], v[194:197], v[26:29]
	v_mfma_f32_16x16x32_bf16 v[22:25], v[160:163], v[202:205], v[22:25]
	v_mfma_f32_16x16x32_bf16 v[18:21], v[168:171], v[202:205], v[18:21]
	s_setprio 1
	s_barrier
	s_add_u32 s82, s82, s10
	s_addc_u32 s83, s83, s11
	s_add_i32 s74, s70, s71
	v_lshl_add_u64 v[228:229], s[82:83], 0, v[132:133]
	s_mov_b32 m0, s74
	v_lshl_add_u64 v[230:231], s[82:83], 0, v[136:137]
	global_load_lds_dwordx4 v[228:229], off
	s_add_i32 m0, s74, 0x2000
	s_nop 0
	global_load_lds_dwordx4 v[230:231], off
	s_waitcnt vmcnt(6)
	s_barrier
	s_setprio 0
	v_mfma_f32_16x16x32_bf16 v[46:49], v[206:209], v[172:175], v[46:49]
	v_mfma_f32_16x16x32_bf16 v[42:45], v[214:217], v[172:175], v[42:45]
	v_mfma_f32_16x16x32_bf16 v[38:41], v[206:209], v[182:185], v[38:41]
	v_mfma_f32_16x16x32_bf16 v[34:37], v[214:217], v[182:185], v[34:37]
	v_mfma_f32_16x16x32_bf16 v[14:17], v[206:209], v[190:193], v[14:17]
	v_mfma_f32_16x16x32_bf16 v[10:13], v[214:217], v[190:193], v[10:13]
	v_mfma_f32_16x16x32_bf16 v[6:9], v[206:209], v[198:201], v[6:9]
	v_mfma_f32_16x16x32_bf16 v[2:5], v[214:217], v[198:201], v[2:5]
	v_mfma_f32_16x16x32_bf16 v[46:49], v[210:213], v[176:179], v[46:49]
	v_mfma_f32_16x16x32_bf16 v[42:45], v[218:221], v[176:179], v[42:45]
	v_mfma_f32_16x16x32_bf16 v[38:41], v[210:213], v[186:189], v[38:41]
	v_mfma_f32_16x16x32_bf16 v[34:37], v[218:221], v[186:189], v[34:37]
	v_mfma_f32_16x16x32_bf16 v[14:17], v[210:213], v[194:197], v[14:17]
	v_mfma_f32_16x16x32_bf16 v[10:13], v[218:221], v[194:197], v[10:13]
	v_mfma_f32_16x16x32_bf16 v[6:9], v[210:213], v[202:205], v[6:9]
	v_mfma_f32_16x16x32_bf16 v[2:5], v[218:221], v[202:205], v[2:5]
	s_setprio 1
	s_add_i32 s74, 0, 0x18000
	v_add_u32_e32 v155, s74, v150
	s_barrier
	ds_read_b128 v[156:159], v155
	ds_read_b128 v[160:163], v155 offset:1024
	ds_read_b128 v[164:167], v155 offset:2048
	ds_read_b128 v[168:171], v155 offset:3072
	s_add_u32 s80, s80, s10
	s_addc_u32 s81, s81, s11
	s_mov_b32 m0, s86
	v_lshl_add_u64 v[206:207], s[80:81], 0, v[130:131]
	ds_read_b128 v[172:175], v153 offset:32768
	ds_read_b128 v[176:179], v153 offset:33792
	ds_read_b128 v[182:185], v153 offset:34816
	ds_read_b128 v[186:189], v153 offset:35840
	ds_read_b128 v[190:193], v153 offset:36864
	ds_read_b128 v[194:197], v153 offset:37888
	ds_read_b128 v[198:201], v153 offset:38912
	ds_read_b128 v[202:205], v153 offset:39936
	global_load_lds_dwordx4 v[206:207], off
	v_lshl_add_u64 v[206:207], s[80:81], 0, v[134:135]
	s_mov_b32 m0, s87
	s_nop 0
	global_load_lds_dwordx4 v[206:207], off
	s_waitcnt lgkmcnt(8)
	s_barrier
	s_waitcnt lgkmcnt(0)
	s_setprio 0
	s_waitcnt lgkmcnt(0)
	v_mfma_f32_16x16x32_bf16 v[126:129], v[156:159], v[172:175], v[126:129]
	v_mfma_f32_16x16x32_bf16 v[122:125], v[164:167], v[172:175], v[122:125]
	v_mfma_f32_16x16x32_bf16 v[118:121], v[156:159], v[182:185], v[118:121]
	v_mfma_f32_16x16x32_bf16 v[114:117], v[164:167], v[182:185], v[114:117]
	v_mfma_f32_16x16x32_bf16 v[94:97], v[156:159], v[190:193], v[94:97]
	v_mfma_f32_16x16x32_bf16 v[90:93], v[164:167], v[190:193], v[90:93]
	v_mfma_f32_16x16x32_bf16 v[86:89], v[156:159], v[198:201], v[86:89]
	v_mfma_f32_16x16x32_bf16 v[82:85], v[164:167], v[198:201], v[82:85]
	v_mfma_f32_16x16x32_bf16 v[126:129], v[160:163], v[176:179], v[126:129]
	v_mfma_f32_16x16x32_bf16 v[122:125], v[168:171], v[176:179], v[122:125]
	v_mfma_f32_16x16x32_bf16 v[118:121], v[160:163], v[186:189], v[118:121]
	v_mfma_f32_16x16x32_bf16 v[114:117], v[168:171], v[186:189], v[114:117]
	v_mfma_f32_16x16x32_bf16 v[94:97], v[160:163], v[194:197], v[94:97]
	v_mfma_f32_16x16x32_bf16 v[90:93], v[168:171], v[194:197], v[90:93]
	v_mfma_f32_16x16x32_bf16 v[86:89], v[160:163], v[202:205], v[86:89]
	v_mfma_f32_16x16x32_bf16 v[82:85], v[168:171], v[202:205], v[82:85]
	s_setprio 1
	s_barrier
	s_add_i32 s75, 0, 0x1c000
	s_add_i32 s74, s74, s71
	v_add_u32_e32 v155, s75, v150
	v_lshl_add_u64 v[148:149], v[148:149], 0, s[14:15]
	s_mov_b32 m0, s74
	ds_read_b128 v[206:209], v155
	ds_read_b128 v[210:213], v155 offset:1024
	ds_read_b128 v[214:217], v155 offset:2048
	ds_read_b128 v[218:221], v155 offset:3072
	global_load_lds_dwordx4 v[148:149], off
	v_lshl_add_u64 v[148:149], v[222:223], 0, s[14:15]
	s_add_i32 m0, s74, 0x2000
	s_nop 0
	global_load_lds_dwordx4 v[148:149], off
	s_barrier
	s_waitcnt lgkmcnt(0)
	s_setprio 0
	s_waitcnt lgkmcnt(0)
	v_mfma_f32_16x16x32_bf16 v[110:113], v[206:209], v[172:175], v[110:113]
	v_mfma_f32_16x16x32_bf16 v[106:109], v[214:217], v[172:175], v[106:109]
	v_mfma_f32_16x16x32_bf16 v[102:105], v[206:209], v[182:185], v[102:105]
	v_mfma_f32_16x16x32_bf16 v[98:101], v[214:217], v[182:185], v[98:101]
	v_mfma_f32_16x16x32_bf16 v[78:81], v[206:209], v[190:193], v[78:81]
	v_mfma_f32_16x16x32_bf16 v[74:77], v[214:217], v[190:193], v[74:77]
	v_mfma_f32_16x16x32_bf16 v[70:73], v[206:209], v[198:201], v[70:73]
	v_mfma_f32_16x16x32_bf16 v[66:69], v[214:217], v[198:201], v[66:69]
	v_mfma_f32_16x16x32_bf16 v[110:113], v[210:213], v[176:179], v[110:113]
	v_mfma_f32_16x16x32_bf16 v[106:109], v[218:221], v[176:179], v[106:109]
	v_mfma_f32_16x16x32_bf16 v[102:105], v[210:213], v[186:189], v[102:105]
	v_mfma_f32_16x16x32_bf16 v[98:101], v[218:221], v[186:189], v[98:101]
	v_mfma_f32_16x16x32_bf16 v[78:81], v[210:213], v[194:197], v[78:81]
	v_mfma_f32_16x16x32_bf16 v[74:77], v[218:221], v[194:197], v[74:77]
	v_mfma_f32_16x16x32_bf16 v[70:73], v[210:213], v[202:205], v[70:73]
	v_mfma_f32_16x16x32_bf16 v[66:69], v[218:221], v[202:205], v[66:69]
	s_setprio 1
	s_mov_b32 m0, s89
	v_lshl_add_u64 v[148:149], v[224:225], 0, s[14:15]
	s_barrier
	ds_read_b128 v[172:175], v153 offset:49152
	ds_read_b128 v[176:179], v153 offset:50176
	ds_read_b128 v[182:185], v153 offset:51200
	ds_read_b128 v[186:189], v153 offset:52224
	ds_read_b128 v[190:193], v153 offset:53248
	ds_read_b128 v[194:197], v153 offset:54272
	ds_read_b128 v[198:201], v153 offset:55296
	ds_read_b128 v[202:205], v153 offset:56320
	global_load_lds_dwordx4 v[148:149], off
	v_lshl_add_u64 v[148:149], v[226:227], 0, s[14:15]
	s_mov_b32 m0, s90
	s_nop 0
	global_load_lds_dwordx4 v[148:149], off
	s_barrier
	s_waitcnt lgkmcnt(0)
	s_setprio 0
	s_waitcnt lgkmcnt(0)
	v_mfma_f32_16x16x32_bf16 v[62:65], v[156:159], v[172:175], v[62:65]
	v_mfma_f32_16x16x32_bf16 v[58:61], v[164:167], v[172:175], v[58:61]
	v_mfma_f32_16x16x32_bf16 v[54:57], v[156:159], v[182:185], v[54:57]
	v_mfma_f32_16x16x32_bf16 v[50:53], v[164:167], v[182:185], v[50:53]
	v_mfma_f32_16x16x32_bf16 v[30:33], v[156:159], v[190:193], v[30:33]
	v_mfma_f32_16x16x32_bf16 v[26:29], v[164:167], v[190:193], v[26:29]
	v_mfma_f32_16x16x32_bf16 v[22:25], v[156:159], v[198:201], v[22:25]
	v_mfma_f32_16x16x32_bf16 v[18:21], v[164:167], v[198:201], v[18:21]
	v_mfma_f32_16x16x32_bf16 v[62:65], v[160:163], v[176:179], v[62:65]
	v_mfma_f32_16x16x32_bf16 v[58:61], v[168:171], v[176:179], v[58:61]
	v_mfma_f32_16x16x32_bf16 v[54:57], v[160:163], v[186:189], v[54:57]
	v_mfma_f32_16x16x32_bf16 v[50:53], v[168:171], v[186:189], v[50:53]
	v_mfma_f32_16x16x32_bf16 v[30:33], v[160:163], v[194:197], v[30:33]
	v_mfma_f32_16x16x32_bf16 v[26:29], v[168:171], v[194:197], v[26:29]
	v_mfma_f32_16x16x32_bf16 v[22:25], v[160:163], v[202:205], v[22:25]
	v_mfma_f32_16x16x32_bf16 v[18:21], v[168:171], v[202:205], v[18:21]
	s_setprio 1
	s_barrier
	s_add_i32 s74, s75, s71
	v_lshl_add_u64 v[148:149], v[228:229], 0, s[14:15]
	s_mov_b32 m0, s74
	s_nop 0
	global_load_lds_dwordx4 v[148:149], off
	v_lshl_add_u64 v[148:149], v[230:231], 0, s[14:15]
	s_add_i32 m0, s74, 0x2000
	s_nop 0
	global_load_lds_dwordx4 v[148:149], off
	s_waitcnt vmcnt(6)
	s_barrier
	s_setprio 0
	v_mfma_f32_16x16x32_bf16 v[46:49], v[206:209], v[172:175], v[46:49]
	v_mfma_f32_16x16x32_bf16 v[42:45], v[214:217], v[172:175], v[42:45]
	v_mfma_f32_16x16x32_bf16 v[38:41], v[206:209], v[182:185], v[38:41]
	v_mfma_f32_16x16x32_bf16 v[34:37], v[214:217], v[182:185], v[34:37]
	v_mfma_f32_16x16x32_bf16 v[14:17], v[206:209], v[190:193], v[14:17]
	v_mfma_f32_16x16x32_bf16 v[10:13], v[214:217], v[190:193], v[10:13]
	v_mfma_f32_16x16x32_bf16 v[6:9], v[206:209], v[198:201], v[6:9]
	v_mfma_f32_16x16x32_bf16 v[2:5], v[214:217], v[198:201], v[2:5]
	v_mfma_f32_16x16x32_bf16 v[46:49], v[210:213], v[176:179], v[46:49]
	v_mfma_f32_16x16x32_bf16 v[42:45], v[218:221], v[176:179], v[42:45]
	v_mfma_f32_16x16x32_bf16 v[38:41], v[210:213], v[186:189], v[38:41]
	v_mfma_f32_16x16x32_bf16 v[34:37], v[218:221], v[186:189], v[34:37]
	v_mfma_f32_16x16x32_bf16 v[14:17], v[210:213], v[194:197], v[14:17]
	v_mfma_f32_16x16x32_bf16 v[10:13], v[218:221], v[194:197], v[10:13]
	v_mfma_f32_16x16x32_bf16 v[6:9], v[210:213], v[202:205], v[6:9]
	v_mfma_f32_16x16x32_bf16 v[2:5], v[218:221], v[202:205], v[2:5]
	s_setprio 1
	s_add_u32 s78, s78, 0x100
	s_addc_u32 s79, s79, 0
	s_add_u32 s73, s73, 0x100
	s_addc_u32 vcc_lo, vcc_lo, 0
	s_cmp_ge_i32 vcc_hi, s91
	s_mov_b32 s80, vcc_hi
	s_barrier
	s_cbranch_scc0 .LBB0_102

.LBB0_470:
	ds_read_b128 v[146:149], v160
	ds_read_b128 v[150:153], v160 offset:1024
	ds_read_b128 v[154:157], v160 offset:2048
	ds_read_b128 v[164:167], v160 offset:3072
	s_add_i32 s90, s62, 2
	s_add_u32 s72, s50, 0x80
	s_addc_u32 s63, s51, 0
	s_cmp_eq_u32 s78, s62
	s_cselect_b32 s62, s0, s72
	s_cselect_b32 s63, s1, s63
	s_cselect_b32 s73, s7, s89
	s_cselect_b32 s72, s6, s88
	v_lshl_add_u64 v[202:203], s[50:51], 0, v[138:139]
	s_add_i32 m0, s69, 0xc000
	ds_read_b128 v[168:171], v161
	ds_read_b128 v[172:175], v161 offset:1024
	ds_read_b128 v[176:179], v161 offset:2048
	ds_read_b128 v[182:185], v161 offset:3072
	ds_read_b128 v[186:189], v161 offset:4096
	ds_read_b128 v[190:193], v161 offset:5120
	ds_read_b128 v[194:197], v161 offset:6144
	ds_read_b128 v[198:201], v161 offset:7168
	global_load_lds_dwordx4 v[202:203], off
	v_lshl_add_u64 v[202:203], s[50:51], 0, v[140:141]
	s_add_i32 m0, s69, 0xe000
	s_nop 0
	global_load_lds_dwordx4 v[202:203], off
	s_waitcnt lgkmcnt(8)
	s_barrier
	s_waitcnt lgkmcnt(0)
	s_setprio 0
	s_waitcnt lgkmcnt(0)
	v_mfma_f32_16x16x32_bf16 v[126:129], v[146:149], v[168:171], v[126:129]
	v_mfma_f32_16x16x32_bf16 v[122:125], v[154:157], v[168:171], v[122:125]
	v_mfma_f32_16x16x32_bf16 v[110:113], v[146:149], v[176:179], v[110:113]
	v_mfma_f32_16x16x32_bf16 v[106:109], v[154:157], v[176:179], v[106:109]
	v_mfma_f32_16x16x32_bf16 v[94:97], v[146:149], v[186:189], v[94:97]
	v_mfma_f32_16x16x32_bf16 v[90:93], v[154:157], v[186:189], v[90:93]
	v_mfma_f32_16x16x32_bf16 v[78:81], v[146:149], v[194:197], v[78:81]
	v_mfma_f32_16x16x32_bf16 v[74:77], v[154:157], v[194:197], v[74:77]
	v_mfma_f32_16x16x32_bf16 v[126:129], v[150:153], v[172:175], v[126:129]
	v_mfma_f32_16x16x32_bf16 v[122:125], v[164:167], v[172:175], v[122:125]
	v_mfma_f32_16x16x32_bf16 v[110:113], v[150:153], v[182:185], v[110:113]
	v_mfma_f32_16x16x32_bf16 v[106:109], v[164:167], v[182:185], v[106:109]
	v_mfma_f32_16x16x32_bf16 v[94:97], v[150:153], v[190:193], v[94:97]
	v_mfma_f32_16x16x32_bf16 v[90:93], v[164:167], v[190:193], v[90:93]
	v_mfma_f32_16x16x32_bf16 v[78:81], v[150:153], v[198:201], v[78:81]
	v_mfma_f32_16x16x32_bf16 v[74:77], v[164:167], v[198:201], v[74:77]
	s_setprio 1
	s_barrier
	s_add_i32 s91, s81, s68
	v_lshl_add_u64 v[218:219], s[72:73], 0, v[132:133]
	s_mov_b32 m0, s91
	ds_read_b128 v[202:205], v162
	ds_read_b128 v[206:209], v162 offset:1024
	ds_read_b128 v[210:213], v162 offset:2048
	ds_read_b128 v[214:217], v162 offset:3072
	global_load_lds_dwordx4 v[218:219], off
	v_lshl_add_u64 v[220:221], s[72:73], 0, v[136:137]
	s_add_i32 m0, s91, 0x2000
	s_nop 0
	global_load_lds_dwordx4 v[220:221], off
	s_barrier
	s_waitcnt lgkmcnt(0)
	s_setprio 0
	s_waitcnt lgkmcnt(0)
	v_mfma_f32_16x16x32_bf16 v[118:121], v[202:205], v[168:171], v[118:121]
	v_mfma_f32_16x16x32_bf16 v[114:117], v[210:213], v[168:171], v[114:117]
	v_mfma_f32_16x16x32_bf16 v[102:105], v[202:205], v[176:179], v[102:105]
	v_mfma_f32_16x16x32_bf16 v[98:101], v[210:213], v[176:179], v[98:101]
	v_mfma_f32_16x16x32_bf16 v[86:89], v[202:205], v[186:189], v[86:89]
	v_mfma_f32_16x16x32_bf16 v[82:85], v[210:213], v[186:189], v[82:85]
	v_mfma_f32_16x16x32_bf16 v[70:73], v[202:205], v[194:197], v[70:73]
	v_mfma_f32_16x16x32_bf16 v[66:69], v[210:213], v[194:197], v[66:69]
	v_mfma_f32_16x16x32_bf16 v[118:121], v[206:209], v[172:175], v[118:121]
	v_mfma_f32_16x16x32_bf16 v[114:117], v[214:217], v[172:175], v[114:117]
	v_mfma_f32_16x16x32_bf16 v[102:105], v[206:209], v[182:185], v[102:105]
	v_mfma_f32_16x16x32_bf16 v[98:101], v[214:217], v[182:185], v[98:101]
	v_mfma_f32_16x16x32_bf16 v[86:89], v[206:209], v[190:193], v[86:89]
	v_mfma_f32_16x16x32_bf16 v[82:85], v[214:217], v[190:193], v[82:85]
	v_mfma_f32_16x16x32_bf16 v[70:73], v[206:209], v[198:201], v[70:73]
	v_mfma_f32_16x16x32_bf16 v[66:69], v[214:217], v[198:201], v[66:69]
	s_setprio 1
	s_mov_b32 m0, s69
	v_lshl_add_u64 v[222:223], s[62:63], 0, v[130:131]
	s_barrier
	ds_read_b128 v[168:171], v161 offset:16384
	ds_read_b128 v[172:175], v161 offset:17408
	ds_read_b128 v[176:179], v161 offset:18432
	ds_read_b128 v[182:185], v161 offset:19456
	ds_read_b128 v[186:189], v161 offset:20480
	ds_read_b128 v[190:193], v161 offset:21504
	ds_read_b128 v[194:197], v161 offset:22528
	ds_read_b128 v[198:201], v161 offset:23552
	global_load_lds_dwordx4 v[222:223], off
	v_lshl_add_u64 v[224:225], s[62:63], 0, v[134:135]
	s_mov_b32 m0, s70
	s_nop 0
	global_load_lds_dwordx4 v[224:225], off
	s_barrier
	s_waitcnt lgkmcnt(0)
	s_setprio 0
	s_waitcnt lgkmcnt(0)
	v_mfma_f32_16x16x32_bf16 v[62:65], v[146:149], v[168:171], v[62:65]
	v_mfma_f32_16x16x32_bf16 v[58:61], v[154:157], v[168:171], v[58:61]
	v_mfma_f32_16x16x32_bf16 v[46:49], v[146:149], v[176:179], v[46:49]
	v_mfma_f32_16x16x32_bf16 v[42:45], v[154:157], v[176:179], v[42:45]
	v_mfma_f32_16x16x32_bf16 v[30:33], v[146:149], v[186:189], v[30:33]
	v_mfma_f32_16x16x32_bf16 v[26:29], v[154:157], v[186:189], v[26:29]
	v_mfma_f32_16x16x32_bf16 v[14:17], v[146:149], v[194:197], v[14:17]
	v_mfma_f32_16x16x32_bf16 v[10:13], v[154:157], v[194:197], v[10:13]
	v_mfma_f32_16x16x32_bf16 v[62:65], v[150:153], v[172:175], v[62:65]
	v_mfma_f32_16x16x32_bf16 v[58:61], v[164:167], v[172:175], v[58:61]
	v_mfma_f32_16x16x32_bf16 v[46:49], v[150:153], v[182:185], v[46:49]
	v_mfma_f32_16x16x32_bf16 v[42:45], v[164:167], v[182:185], v[42:45]
	v_mfma_f32_16x16x32_bf16 v[30:33], v[150:153], v[190:193], v[30:33]
	v_mfma_f32_16x16x32_bf16 v[26:29], v[164:167], v[190:193], v[26:29]
	v_mfma_f32_16x16x32_bf16 v[14:17], v[150:153], v[198:201], v[14:17]
	v_mfma_f32_16x16x32_bf16 v[10:13], v[164:167], v[198:201], v[10:13]
	s_setprio 1
	s_barrier
	s_add_u32 s72, s72, s10
	s_addc_u32 s73, s73, s11
	s_add_i32 s91, s82, s68
	v_lshl_add_u64 v[226:227], s[72:73], 0, v[132:133]
	s_mov_b32 m0, s91
	v_lshl_add_u64 v[228:229], s[72:73], 0, v[136:137]
	global_load_lds_dwordx4 v[226:227], off
	s_add_i32 m0, s91, 0x2000
	s_nop 0
	global_load_lds_dwordx4 v[228:229], off
	s_waitcnt vmcnt(6)
	s_barrier
	s_setprio 0
	v_mfma_f32_16x16x32_bf16 v[54:57], v[202:205], v[168:171], v[54:57]
	v_mfma_f32_16x16x32_bf16 v[50:53], v[210:213], v[168:171], v[50:53]
	v_mfma_f32_16x16x32_bf16 v[38:41], v[202:205], v[176:179], v[38:41]
	v_mfma_f32_16x16x32_bf16 v[34:37], v[210:213], v[176:179], v[34:37]
	v_mfma_f32_16x16x32_bf16 v[22:25], v[202:205], v[186:189], v[22:25]
	v_mfma_f32_16x16x32_bf16 v[18:21], v[210:213], v[186:189], v[18:21]
	v_mfma_f32_16x16x32_bf16 v[6:9], v[202:205], v[194:197], v[6:9]
	v_mfma_f32_16x16x32_bf16 v[2:5], v[210:213], v[194:197], v[2:5]
	v_mfma_f32_16x16x32_bf16 v[54:57], v[206:209], v[172:175], v[54:57]
	v_mfma_f32_16x16x32_bf16 v[50:53], v[214:217], v[172:175], v[50:53]
	v_mfma_f32_16x16x32_bf16 v[38:41], v[206:209], v[182:185], v[38:41]
	v_mfma_f32_16x16x32_bf16 v[34:37], v[214:217], v[182:185], v[34:37]
	v_mfma_f32_16x16x32_bf16 v[22:25], v[206:209], v[190:193], v[22:25]
	v_mfma_f32_16x16x32_bf16 v[18:21], v[214:217], v[190:193], v[18:21]
	v_mfma_f32_16x16x32_bf16 v[6:9], v[206:209], v[198:201], v[6:9]
	v_mfma_f32_16x16x32_bf16 v[2:5], v[214:217], v[198:201], v[2:5]
	s_setprio 1
	s_add_i32 s72, 0, 0x18000
	v_add_u32_e32 v163, s72, v158
	s_barrier
	ds_read_b128 v[146:149], v163
	ds_read_b128 v[150:153], v163 offset:1024
	ds_read_b128 v[154:157], v163 offset:2048
	ds_read_b128 v[164:167], v163 offset:3072
	s_add_u32 s62, s62, s10
	s_addc_u32 s63, s63, s11
	s_mov_b32 m0, s3
	v_lshl_add_u64 v[202:203], s[62:63], 0, v[130:131]
	ds_read_b128 v[168:171], v161 offset:32768
	ds_read_b128 v[172:175], v161 offset:33792
	ds_read_b128 v[176:179], v161 offset:34816
	ds_read_b128 v[182:185], v161 offset:35840
	ds_read_b128 v[186:189], v161 offset:36864
	ds_read_b128 v[190:193], v161 offset:37888
	ds_read_b128 v[194:197], v161 offset:38912
	ds_read_b128 v[198:201], v161 offset:39936
	global_load_lds_dwordx4 v[202:203], off
	v_lshl_add_u64 v[202:203], s[62:63], 0, v[134:135]
	s_mov_b32 m0, s71
	s_nop 0
	global_load_lds_dwordx4 v[202:203], off
	s_waitcnt lgkmcnt(8)
	s_barrier
	s_waitcnt lgkmcnt(0)
	s_setprio 0
	s_waitcnt lgkmcnt(0)
	v_mfma_f32_16x16x32_bf16 v[126:129], v[146:149], v[168:171], v[126:129]
	v_mfma_f32_16x16x32_bf16 v[122:125], v[154:157], v[168:171], v[122:125]
	v_mfma_f32_16x16x32_bf16 v[110:113], v[146:149], v[176:179], v[110:113]
	v_mfma_f32_16x16x32_bf16 v[106:109], v[154:157], v[176:179], v[106:109]
	v_mfma_f32_16x16x32_bf16 v[94:97], v[146:149], v[186:189], v[94:97]
	v_mfma_f32_16x16x32_bf16 v[90:93], v[154:157], v[186:189], v[90:93]
	v_mfma_f32_16x16x32_bf16 v[78:81], v[146:149], v[194:197], v[78:81]
	v_mfma_f32_16x16x32_bf16 v[74:77], v[154:157], v[194:197], v[74:77]
	v_mfma_f32_16x16x32_bf16 v[126:129], v[150:153], v[172:175], v[126:129]
	v_mfma_f32_16x16x32_bf16 v[122:125], v[164:167], v[172:175], v[122:125]
	v_mfma_f32_16x16x32_bf16 v[110:113], v[150:153], v[182:185], v[110:113]
	v_mfma_f32_16x16x32_bf16 v[106:109], v[164:167], v[182:185], v[106:109]
	v_mfma_f32_16x16x32_bf16 v[94:97], v[150:153], v[190:193], v[94:97]
	v_mfma_f32_16x16x32_bf16 v[90:93], v[164:167], v[190:193], v[90:93]
	v_mfma_f32_16x16x32_bf16 v[78:81], v[150:153], v[198:201], v[78:81]
	v_mfma_f32_16x16x32_bf16 v[74:77], v[164:167], v[198:201], v[74:77]
	s_setprio 1
	s_barrier
	s_add_i32 s62, 0, 0x1c000
	s_add_i32 s63, s72, s68
	v_add_u32_e32 v163, s62, v158
	v_lshl_add_u64 v[218:219], v[218:219], 0, s[14:15]
	s_mov_b32 m0, s63
	ds_read_b128 v[202:205], v163
	ds_read_b128 v[206:209], v163 offset:1024
	ds_read_b128 v[210:213], v163 offset:2048
	ds_read_b128 v[214:217], v163 offset:3072
	global_load_lds_dwordx4 v[218:219], off
	v_lshl_add_u64 v[218:219], v[220:221], 0, s[14:15]
	s_add_i32 m0, s63, 0x2000
	s_nop 0
	global_load_lds_dwordx4 v[218:219], off
	s_barrier
	s_waitcnt lgkmcnt(0)
	s_setprio 0
	s_waitcnt lgkmcnt(0)
	v_mfma_f32_16x16x32_bf16 v[118:121], v[202:205], v[168:171], v[118:121]
	v_mfma_f32_16x16x32_bf16 v[114:117], v[210:213], v[168:171], v[114:117]
	v_mfma_f32_16x16x32_bf16 v[102:105], v[202:205], v[176:179], v[102:105]
	v_mfma_f32_16x16x32_bf16 v[98:101], v[210:213], v[176:179], v[98:101]
	v_mfma_f32_16x16x32_bf16 v[86:89], v[202:205], v[186:189], v[86:89]
	v_mfma_f32_16x16x32_bf16 v[82:85], v[210:213], v[186:189], v[82:85]
	v_mfma_f32_16x16x32_bf16 v[70:73], v[202:205], v[194:197], v[70:73]
	v_mfma_f32_16x16x32_bf16 v[66:69], v[210:213], v[194:197], v[66:69]
	v_mfma_f32_16x16x32_bf16 v[118:121], v[206:209], v[172:175], v[118:121]
	v_mfma_f32_16x16x32_bf16 v[114:117], v[214:217], v[172:175], v[114:117]
	v_mfma_f32_16x16x32_bf16 v[102:105], v[206:209], v[182:185], v[102:105]
	v_mfma_f32_16x16x32_bf16 v[98:101], v[214:217], v[182:185], v[98:101]
	v_mfma_f32_16x16x32_bf16 v[86:89], v[206:209], v[190:193], v[86:89]
	v_mfma_f32_16x16x32_bf16 v[82:85], v[214:217], v[190:193], v[82:85]
	v_mfma_f32_16x16x32_bf16 v[70:73], v[206:209], v[198:201], v[70:73]
	v_mfma_f32_16x16x32_bf16 v[66:69], v[214:217], v[198:201], v[66:69]
	s_setprio 1
	s_mov_b32 m0, s75
	v_lshl_add_u64 v[218:219], v[222:223], 0, s[14:15]
	s_barrier
	ds_read_b128 v[168:171], v161 offset:49152
	ds_read_b128 v[172:175], v161 offset:50176
	ds_read_b128 v[176:179], v161 offset:51200
	ds_read_b128 v[182:185], v161 offset:52224
	ds_read_b128 v[186:189], v161 offset:53248
	ds_read_b128 v[190:193], v161 offset:54272
	ds_read_b128 v[194:197], v161 offset:55296
	ds_read_b128 v[198:201], v161 offset:56320
	global_load_lds_dwordx4 v[218:219], off
	v_lshl_add_u64 v[218:219], v[224:225], 0, s[14:15]
	s_mov_b32 m0, s76
	s_nop 0
	global_load_lds_dwordx4 v[218:219], off
	s_barrier
	s_waitcnt lgkmcnt(0)
	s_setprio 0
	s_waitcnt lgkmcnt(0)
	v_mfma_f32_16x16x32_bf16 v[62:65], v[146:149], v[168:171], v[62:65]
	v_mfma_f32_16x16x32_bf16 v[58:61], v[154:157], v[168:171], v[58:61]
	v_mfma_f32_16x16x32_bf16 v[46:49], v[146:149], v[176:179], v[46:49]
	v_mfma_f32_16x16x32_bf16 v[42:45], v[154:157], v[176:179], v[42:45]
	v_mfma_f32_16x16x32_bf16 v[30:33], v[146:149], v[186:189], v[30:33]
	v_mfma_f32_16x16x32_bf16 v[26:29], v[154:157], v[186:189], v[26:29]
	v_mfma_f32_16x16x32_bf16 v[14:17], v[146:149], v[194:197], v[14:17]
	v_mfma_f32_16x16x32_bf16 v[10:13], v[154:157], v[194:197], v[10:13]
	v_mfma_f32_16x16x32_bf16 v[62:65], v[150:153], v[172:175], v[62:65]
	v_mfma_f32_16x16x32_bf16 v[58:61], v[164:167], v[172:175], v[58:61]
	v_mfma_f32_16x16x32_bf16 v[46:49], v[150:153], v[182:185], v[46:49]
	v_mfma_f32_16x16x32_bf16 v[42:45], v[164:167], v[182:185], v[42:45]
	v_mfma_f32_16x16x32_bf16 v[30:33], v[150:153], v[190:193], v[30:33]
	v_mfma_f32_16x16x32_bf16 v[26:29], v[164:167], v[190:193], v[26:29]
	v_mfma_f32_16x16x32_bf16 v[14:17], v[150:153], v[198:201], v[14:17]
	v_mfma_f32_16x16x32_bf16 v[10:13], v[164:167], v[198:201], v[10:13]
	s_setprio 1
	s_barrier
	s_add_i32 s62, s62, s68
	v_lshl_add_u64 v[146:147], v[226:227], 0, s[14:15]
	s_mov_b32 m0, s62
	s_nop 0
	global_load_lds_dwordx4 v[146:147], off
	v_lshl_add_u64 v[146:147], v[228:229], 0, s[14:15]
	s_add_i32 m0, s62, 0x2000
	s_nop 0
	global_load_lds_dwordx4 v[146:147], off
	s_waitcnt vmcnt(6)
	s_barrier
	s_setprio 0
	v_mfma_f32_16x16x32_bf16 v[54:57], v[202:205], v[168:171], v[54:57]
	v_mfma_f32_16x16x32_bf16 v[50:53], v[210:213], v[168:171], v[50:53]
	v_mfma_f32_16x16x32_bf16 v[38:41], v[202:205], v[176:179], v[38:41]
	v_mfma_f32_16x16x32_bf16 v[34:37], v[210:213], v[176:179], v[34:37]
	v_mfma_f32_16x16x32_bf16 v[22:25], v[202:205], v[186:189], v[22:25]
	v_mfma_f32_16x16x32_bf16 v[18:21], v[210:213], v[186:189], v[18:21]
	v_mfma_f32_16x16x32_bf16 v[6:9], v[202:205], v[194:197], v[6:9]
	v_mfma_f32_16x16x32_bf16 v[2:5], v[210:213], v[194:197], v[2:5]
	v_mfma_f32_16x16x32_bf16 v[54:57], v[206:209], v[172:175], v[54:57]
	v_mfma_f32_16x16x32_bf16 v[50:53], v[214:217], v[172:175], v[50:53]
	v_mfma_f32_16x16x32_bf16 v[38:41], v[206:209], v[182:185], v[38:41]
	v_mfma_f32_16x16x32_bf16 v[34:37], v[214:217], v[182:185], v[34:37]
	v_mfma_f32_16x16x32_bf16 v[22:25], v[206:209], v[190:193], v[22:25]
	v_mfma_f32_16x16x32_bf16 v[18:21], v[214:217], v[190:193], v[18:21]
	v_mfma_f32_16x16x32_bf16 v[6:9], v[206:209], v[198:201], v[6:9]
	v_mfma_f32_16x16x32_bf16 v[2:5], v[214:217], v[198:201], v[2:5]
	s_setprio 1
	s_add_u32 s50, s50, 0x100
	s_addc_u32 s51, s51, 0
	s_add_u32 s88, s88, 0x100
	s_addc_u32 s89, s89, 0
	s_cmp_ge_i32 s90, s77
	s_mov_b32 s62, s90
	s_barrier
	s_cbranch_scc0 .LBB0_470

.LBB0_678:
	s_add_i32 s68, s68, 2
	s_and_b64 s[64:65], exec, s[64:65]
	s_cselect_b32 s65, s53, s97
	s_cselect_b32 s64, s52, s96
	s_add_i32 s3, 0, 0x10000
	v_add_u32_e32 v1, s3, v196
	ds_read_b128 v[132:135], v1
	ds_read_b128 v[136:139], v1 offset:1024
	ds_read_b128 v[140:143], v1 offset:2048
	ds_read_b128 v[144:147], v1 offset:3072
	s_add_u32 s62, s62, 0x20000
	s_addc_u32 s63, s63, 0
	v_lshl_add_u64 v[2:3], s[62:63], 0, v[182:183]
	s_add_i32 m0, s70, 0xc000
	ds_read_b128 v[148:151], v197
	ds_read_b128 v[152:155], v197 offset:1024
	ds_read_b128 v[156:159], v197 offset:2048
	ds_read_b128 v[160:163], v197 offset:3072
	ds_read_b128 v[164:167], v197 offset:4096
	ds_read_b128 v[168:171], v197 offset:5120
	ds_read_b128 v[172:175], v197 offset:6144
	ds_read_b128 v[176:179], v197 offset:7168
	global_load_lds_dwordx4 v[2:3], off
	v_lshl_add_u64 v[2:3], s[62:63], 0, v[186:187]
	s_add_i32 m0, s70, 0xe000
	s_nop 0
	global_load_lds_dwordx4 v[2:3], off
	s_waitcnt lgkmcnt(8)
	s_barrier
	s_waitcnt lgkmcnt(0)
	s_setprio 0
	s_waitcnt lgkmcnt(0)
	v_mfma_f32_16x16x32_bf16 v[124:127], v[132:135], v[148:151], v[124:127]
	v_mfma_f32_16x16x32_bf16 v[128:131], v[140:143], v[148:151], v[128:131]
	v_mfma_f32_16x16x32_bf16 v[108:111], v[132:135], v[156:159], v[108:111]
	v_mfma_f32_16x16x32_bf16 v[112:115], v[140:143], v[156:159], v[112:115]
	v_mfma_f32_16x16x32_bf16 v[92:95], v[132:135], v[164:167], v[92:95]
	v_mfma_f32_16x16x32_bf16 v[96:99], v[140:143], v[164:167], v[96:99]
	v_mfma_f32_16x16x32_bf16 v[76:79], v[132:135], v[172:175], v[76:79]
	v_mfma_f32_16x16x32_bf16 v[80:83], v[140:143], v[172:175], v[80:83]
	v_mfma_f32_16x16x32_bf16 v[124:127], v[136:139], v[152:155], v[124:127]
	v_mfma_f32_16x16x32_bf16 v[128:131], v[144:147], v[152:155], v[128:131]
	v_mfma_f32_16x16x32_bf16 v[108:111], v[136:139], v[160:163], v[108:111]
	v_mfma_f32_16x16x32_bf16 v[112:115], v[144:147], v[160:163], v[112:115]
	v_mfma_f32_16x16x32_bf16 v[92:95], v[136:139], v[168:171], v[92:95]
	v_mfma_f32_16x16x32_bf16 v[96:99], v[144:147], v[168:171], v[96:99]
	v_mfma_f32_16x16x32_bf16 v[76:79], v[136:139], v[176:179], v[76:79]
	v_mfma_f32_16x16x32_bf16 v[80:83], v[144:147], v[176:179], v[80:83]
	s_setprio 1
	s_barrier
	s_add_i32 s3, s3, s67
	v_add_u32_e32 v1, s90, v196
	v_lshl_add_u64 v[214:215], s[64:65], 0, v[184:185]
	s_mov_b32 m0, s3
	ds_read_b128 v[198:201], v1
	ds_read_b128 v[202:205], v1 offset:1024
	ds_read_b128 v[206:209], v1 offset:2048
	ds_read_b128 v[210:213], v1 offset:3072
	global_load_lds_dwordx4 v[214:215], off
	v_lshl_add_u64 v[216:217], s[64:65], 0, v[188:189]
	s_add_i32 m0, s3, 0x2000
	s_nop 0
	global_load_lds_dwordx4 v[216:217], off
	s_barrier
	s_waitcnt lgkmcnt(0)
	s_setprio 0
	s_waitcnt lgkmcnt(0)
	v_mfma_f32_16x16x32_bf16 v[116:119], v[198:201], v[148:151], v[116:119]
	v_mfma_f32_16x16x32_bf16 v[120:123], v[206:209], v[148:151], v[120:123]
	v_mfma_f32_16x16x32_bf16 v[100:103], v[198:201], v[156:159], v[100:103]
	v_mfma_f32_16x16x32_bf16 v[104:107], v[206:209], v[156:159], v[104:107]
	v_mfma_f32_16x16x32_bf16 v[84:87], v[198:201], v[164:167], v[84:87]
	v_mfma_f32_16x16x32_bf16 v[88:91], v[206:209], v[164:167], v[88:91]
	v_mfma_f32_16x16x32_bf16 v[68:71], v[198:201], v[172:175], v[68:71]
	v_mfma_f32_16x16x32_bf16 v[72:75], v[206:209], v[172:175], v[72:75]
	v_mfma_f32_16x16x32_bf16 v[116:119], v[202:205], v[152:155], v[116:119]
	v_mfma_f32_16x16x32_bf16 v[120:123], v[210:213], v[152:155], v[120:123]
	v_mfma_f32_16x16x32_bf16 v[100:103], v[202:205], v[160:163], v[100:103]
	v_mfma_f32_16x16x32_bf16 v[104:107], v[210:213], v[160:163], v[104:107]
	v_mfma_f32_16x16x32_bf16 v[84:87], v[202:205], v[168:171], v[84:87]
	v_mfma_f32_16x16x32_bf16 v[88:91], v[210:213], v[168:171], v[88:91]
	v_mfma_f32_16x16x32_bf16 v[68:71], v[202:205], v[176:179], v[68:71]
	v_mfma_f32_16x16x32_bf16 v[72:75], v[210:213], v[176:179], v[72:75]
	s_setprio 1
	s_mov_b32 m0, s70
	v_lshl_add_u64 v[218:219], s[60:61], 0, v[182:183]
	s_barrier
	ds_read_b128 v[148:151], v197 offset:16384
	ds_read_b128 v[152:155], v197 offset:17408
	ds_read_b128 v[156:159], v197 offset:18432
	ds_read_b128 v[160:163], v197 offset:19456
	ds_read_b128 v[164:167], v197 offset:20480
	ds_read_b128 v[168:171], v197 offset:21504
	ds_read_b128 v[172:175], v197 offset:22528
	ds_read_b128 v[176:179], v197 offset:23552
	global_load_lds_dwordx4 v[218:219], off
	v_lshl_add_u64 v[220:221], s[60:61], 0, v[186:187]
	s_mov_b32 m0, s71
	s_nop 0
	global_load_lds_dwordx4 v[220:221], off
	s_barrier
	s_waitcnt lgkmcnt(0)
	s_setprio 0
	s_waitcnt lgkmcnt(0)
	v_mfma_f32_16x16x32_bf16 v[60:63], v[132:135], v[148:151], v[60:63]
	v_mfma_f32_16x16x32_bf16 v[64:67], v[140:143], v[148:151], v[64:67]
	v_mfma_f32_16x16x32_bf16 v[44:47], v[132:135], v[156:159], v[44:47]
	v_mfma_f32_16x16x32_bf16 v[48:51], v[140:143], v[156:159], v[48:51]
	v_mfma_f32_16x16x32_bf16 v[28:31], v[132:135], v[164:167], v[28:31]
	v_mfma_f32_16x16x32_bf16 v[32:35], v[140:143], v[164:167], v[32:35]
	v_mfma_f32_16x16x32_bf16 v[12:15], v[132:135], v[172:175], v[12:15]
	v_mfma_f32_16x16x32_bf16 v[16:19], v[140:143], v[172:175], v[16:19]
	v_mfma_f32_16x16x32_bf16 v[60:63], v[136:139], v[152:155], v[60:63]
	v_mfma_f32_16x16x32_bf16 v[64:67], v[144:147], v[152:155], v[64:67]
	v_mfma_f32_16x16x32_bf16 v[44:47], v[136:139], v[160:163], v[44:47]
	v_mfma_f32_16x16x32_bf16 v[48:51], v[144:147], v[160:163], v[48:51]
	v_mfma_f32_16x16x32_bf16 v[28:31], v[136:139], v[168:171], v[28:31]
	v_mfma_f32_16x16x32_bf16 v[32:35], v[144:147], v[168:171], v[32:35]
	v_mfma_f32_16x16x32_bf16 v[12:15], v[136:139], v[176:179], v[12:15]
	v_mfma_f32_16x16x32_bf16 v[16:19], v[144:147], v[176:179], v[16:19]
	s_setprio 1
	s_barrier
	s_add_u32 s62, s64, s8
	s_addc_u32 s63, s65, s9
	s_add_i32 s3, s90, s67
	v_lshl_add_u64 v[222:223], s[62:63], 0, v[184:185]
	s_mov_b32 m0, s3
	v_lshl_add_u64 v[224:225], s[62:63], 0, v[188:189]
	global_load_lds_dwordx4 v[222:223], off
	s_add_i32 m0, s3, 0x2000
	s_nop 0
	global_load_lds_dwordx4 v[224:225], off
	s_waitcnt vmcnt(6)
	s_barrier
	s_setprio 0
	v_mfma_f32_16x16x32_bf16 v[52:55], v[198:201], v[148:151], v[52:55]
	v_mfma_f32_16x16x32_bf16 v[56:59], v[206:209], v[148:151], v[56:59]
	v_mfma_f32_16x16x32_bf16 v[36:39], v[198:201], v[156:159], v[36:39]
	v_mfma_f32_16x16x32_bf16 v[40:43], v[206:209], v[156:159], v[40:43]
	v_mfma_f32_16x16x32_bf16 v[20:23], v[198:201], v[164:167], v[20:23]
	v_mfma_f32_16x16x32_bf16 v[24:27], v[206:209], v[164:167], v[24:27]
	v_mfma_f32_16x16x32_bf16 v[2:5], v[198:201], v[172:175], v[4:7]
	v_mfma_f32_16x16x32_bf16 v[6:9], v[206:209], v[172:175], v[8:11]
	v_mfma_f32_16x16x32_bf16 v[52:55], v[202:205], v[152:155], v[52:55]
	v_mfma_f32_16x16x32_bf16 v[56:59], v[210:213], v[152:155], v[56:59]
	v_mfma_f32_16x16x32_bf16 v[36:39], v[202:205], v[160:163], v[36:39]
	v_mfma_f32_16x16x32_bf16 v[40:43], v[210:213], v[160:163], v[40:43]
	v_mfma_f32_16x16x32_bf16 v[20:23], v[202:205], v[168:171], v[20:23]
	v_mfma_f32_16x16x32_bf16 v[24:27], v[210:213], v[168:171], v[24:27]
	v_mfma_f32_16x16x32_bf16 v[2:5], v[202:205], v[176:179], v[2:5]
	v_mfma_f32_16x16x32_bf16 v[8:11], v[210:213], v[176:179], v[6:9]
	s_setprio 1
	s_add_i32 s3, 0, 0x18000
	v_add_u32_e32 v1, s3, v196
	s_barrier
	ds_read_b128 v[132:135], v1
	ds_read_b128 v[136:139], v1 offset:1024
	ds_read_b128 v[140:143], v1 offset:2048
	ds_read_b128 v[144:147], v1 offset:3072
	s_add_u32 s60, s60, 0x20000
	s_addc_u32 s61, s61, 0
	s_mov_b32 m0, s72
	v_lshl_add_u64 v[6:7], s[60:61], 0, v[182:183]
	ds_read_b128 v[148:151], v197 offset:32768
	ds_read_b128 v[152:155], v197 offset:33792
	ds_read_b128 v[156:159], v197 offset:34816
	ds_read_b128 v[160:163], v197 offset:35840
	ds_read_b128 v[164:167], v197 offset:36864
	ds_read_b128 v[168:171], v197 offset:37888
	ds_read_b128 v[172:175], v197 offset:38912
	ds_read_b128 v[176:179], v197 offset:39936
	global_load_lds_dwordx4 v[6:7], off
	v_lshl_add_u64 v[6:7], s[60:61], 0, v[186:187]
	s_mov_b32 m0, s73
	s_nop 0
	global_load_lds_dwordx4 v[6:7], off
	s_waitcnt lgkmcnt(8)
	s_barrier
	s_waitcnt lgkmcnt(0)
	s_setprio 0
	s_waitcnt lgkmcnt(0)
	v_mfma_f32_16x16x32_bf16 v[124:127], v[132:135], v[148:151], v[124:127]
	v_mfma_f32_16x16x32_bf16 v[128:131], v[140:143], v[148:151], v[128:131]
	v_mfma_f32_16x16x32_bf16 v[108:111], v[132:135], v[156:159], v[108:111]
	v_mfma_f32_16x16x32_bf16 v[112:115], v[140:143], v[156:159], v[112:115]
	v_mfma_f32_16x16x32_bf16 v[92:95], v[132:135], v[164:167], v[92:95]
	v_mfma_f32_16x16x32_bf16 v[96:99], v[140:143], v[164:167], v[96:99]
	v_mfma_f32_16x16x32_bf16 v[76:79], v[132:135], v[172:175], v[76:79]
	v_mfma_f32_16x16x32_bf16 v[80:83], v[140:143], v[172:175], v[80:83]
	v_mfma_f32_16x16x32_bf16 v[124:127], v[136:139], v[152:155], v[124:127]
	v_mfma_f32_16x16x32_bf16 v[128:131], v[144:147], v[152:155], v[128:131]
	v_mfma_f32_16x16x32_bf16 v[108:111], v[136:139], v[160:163], v[108:111]
	v_mfma_f32_16x16x32_bf16 v[112:115], v[144:147], v[160:163], v[112:115]
	v_mfma_f32_16x16x32_bf16 v[92:95], v[136:139], v[168:171], v[92:95]
	v_mfma_f32_16x16x32_bf16 v[96:99], v[144:147], v[168:171], v[96:99]
	v_mfma_f32_16x16x32_bf16 v[76:79], v[136:139], v[176:179], v[76:79]
	v_mfma_f32_16x16x32_bf16 v[80:83], v[144:147], v[176:179], v[80:83]
	s_setprio 1
	s_barrier
	s_add_i32 s12, 0, 0x1c000
	s_add_i32 s3, s3, s67
	v_add_u32_e32 v1, s12, v196
	v_lshl_add_u64 v[6:7], v[214:215], 0, s[14:15]
	s_mov_b32 m0, s3
	ds_read_b128 v[198:201], v1
	ds_read_b128 v[202:205], v1 offset:1024
	ds_read_b128 v[206:209], v1 offset:2048
	ds_read_b128 v[210:213], v1 offset:3072
	global_load_lds_dwordx4 v[6:7], off
	v_lshl_add_u64 v[6:7], v[216:217], 0, s[14:15]
	s_add_i32 m0, s3, 0x2000
	s_nop 0
	global_load_lds_dwordx4 v[6:7], off
	s_barrier
	s_waitcnt lgkmcnt(0)
	s_setprio 0
	s_waitcnt lgkmcnt(0)
	v_mfma_f32_16x16x32_bf16 v[116:119], v[198:201], v[148:151], v[116:119]
	v_mfma_f32_16x16x32_bf16 v[120:123], v[206:209], v[148:151], v[120:123]
	v_mfma_f32_16x16x32_bf16 v[100:103], v[198:201], v[156:159], v[100:103]
	v_mfma_f32_16x16x32_bf16 v[104:107], v[206:209], v[156:159], v[104:107]
	v_mfma_f32_16x16x32_bf16 v[84:87], v[198:201], v[164:167], v[84:87]
	v_mfma_f32_16x16x32_bf16 v[88:91], v[206:209], v[164:167], v[88:91]
	v_mfma_f32_16x16x32_bf16 v[68:71], v[198:201], v[172:175], v[68:71]
	v_mfma_f32_16x16x32_bf16 v[72:75], v[206:209], v[172:175], v[72:75]
	v_mfma_f32_16x16x32_bf16 v[116:119], v[202:205], v[152:155], v[116:119]
	v_mfma_f32_16x16x32_bf16 v[120:123], v[210:213], v[152:155], v[120:123]
	v_mfma_f32_16x16x32_bf16 v[100:103], v[202:205], v[160:163], v[100:103]
	v_mfma_f32_16x16x32_bf16 v[104:107], v[210:213], v[160:163], v[104:107]
	v_mfma_f32_16x16x32_bf16 v[84:87], v[202:205], v[168:171], v[84:87]
	v_mfma_f32_16x16x32_bf16 v[88:91], v[210:213], v[168:171], v[88:91]
	v_mfma_f32_16x16x32_bf16 v[68:71], v[202:205], v[176:179], v[68:71]
	v_mfma_f32_16x16x32_bf16 v[72:75], v[210:213], v[176:179], v[72:75]
	s_setprio 1
	s_mov_b32 m0, s76
	v_lshl_add_u64 v[6:7], v[218:219], 0, s[14:15]
	s_barrier
	ds_read_b128 v[148:151], v197 offset:49152
	ds_read_b128 v[152:155], v197 offset:50176
	ds_read_b128 v[156:159], v197 offset:51200
	ds_read_b128 v[160:163], v197 offset:52224
	ds_read_b128 v[164:167], v197 offset:53248
	ds_read_b128 v[168:171], v197 offset:54272
	ds_read_b128 v[172:175], v197 offset:55296
	ds_read_b128 v[176:179], v197 offset:56320
	global_load_lds_dwordx4 v[6:7], off
	v_lshl_add_u64 v[6:7], v[220:221], 0, s[14:15]
	s_mov_b32 m0, s77
	s_nop 0
	global_load_lds_dwordx4 v[6:7], off
	s_barrier
	s_waitcnt lgkmcnt(0)
	s_setprio 0
	s_waitcnt lgkmcnt(0)
	v_mfma_f32_16x16x32_bf16 v[60:63], v[132:135], v[148:151], v[60:63]
	v_mfma_f32_16x16x32_bf16 v[64:67], v[140:143], v[148:151], v[64:67]
	v_mfma_f32_16x16x32_bf16 v[44:47], v[132:135], v[156:159], v[44:47]
	v_mfma_f32_16x16x32_bf16 v[48:51], v[140:143], v[156:159], v[48:51]
	v_mfma_f32_16x16x32_bf16 v[28:31], v[132:135], v[164:167], v[28:31]
	v_mfma_f32_16x16x32_bf16 v[32:35], v[140:143], v[164:167], v[32:35]
	v_mfma_f32_16x16x32_bf16 v[12:15], v[132:135], v[172:175], v[12:15]
	v_mfma_f32_16x16x32_bf16 v[16:19], v[140:143], v[172:175], v[16:19]
	v_mfma_f32_16x16x32_bf16 v[60:63], v[136:139], v[152:155], v[60:63]
	v_mfma_f32_16x16x32_bf16 v[64:67], v[144:147], v[152:155], v[64:67]
	v_mfma_f32_16x16x32_bf16 v[44:47], v[136:139], v[160:163], v[44:47]
	v_mfma_f32_16x16x32_bf16 v[48:51], v[144:147], v[160:163], v[48:51]
	v_mfma_f32_16x16x32_bf16 v[28:31], v[136:139], v[168:171], v[28:31]
	v_mfma_f32_16x16x32_bf16 v[32:35], v[144:147], v[168:171], v[32:35]
	v_mfma_f32_16x16x32_bf16 v[12:15], v[136:139], v[176:179], v[12:15]
	v_mfma_f32_16x16x32_bf16 v[16:19], v[144:147], v[176:179], v[16:19]
	s_setprio 1
	s_barrier
	s_add_i32 s3, s12, s67
	v_lshl_add_u64 v[6:7], v[222:223], 0, s[14:15]
	s_mov_b32 m0, s3
	s_nop 0
	global_load_lds_dwordx4 v[6:7], off
	v_lshl_add_u64 v[6:7], v[224:225], 0, s[14:15]
	s_add_i32 m0, s3, 0x2000
	s_nop 0
	global_load_lds_dwordx4 v[6:7], off
	s_waitcnt vmcnt(6)
	s_barrier
	s_setprio 0
	v_mfma_f32_16x16x32_bf16 v[52:55], v[198:201], v[148:151], v[52:55]
	v_mfma_f32_16x16x32_bf16 v[56:59], v[206:209], v[148:151], v[56:59]
	v_mfma_f32_16x16x32_bf16 v[36:39], v[198:201], v[156:159], v[36:39]
	v_mfma_f32_16x16x32_bf16 v[40:43], v[206:209], v[156:159], v[40:43]
	v_mfma_f32_16x16x32_bf16 v[20:23], v[198:201], v[164:167], v[20:23]
	v_mfma_f32_16x16x32_bf16 v[24:27], v[206:209], v[164:167], v[24:27]
	v_mfma_f32_16x16x32_bf16 v[2:5], v[198:201], v[172:175], v[2:5]
	v_mfma_f32_16x16x32_bf16 v[8:11], v[206:209], v[172:175], v[8:11]
	v_mfma_f32_16x16x32_bf16 v[52:55], v[202:205], v[152:155], v[52:55]
	v_mfma_f32_16x16x32_bf16 v[56:59], v[210:213], v[152:155], v[56:59]
	v_mfma_f32_16x16x32_bf16 v[36:39], v[202:205], v[160:163], v[36:39]
	v_mfma_f32_16x16x32_bf16 v[40:43], v[210:213], v[160:163], v[40:43]
	v_mfma_f32_16x16x32_bf16 v[20:23], v[202:205], v[168:171], v[20:23]
	v_mfma_f32_16x16x32_bf16 v[24:27], v[210:213], v[168:171], v[24:27]
	v_mfma_f32_16x16x32_bf16 v[4:7], v[202:205], v[176:179], v[2:5]
	v_mfma_f32_16x16x32_bf16 v[8:11], v[210:213], v[176:179], v[8:11]
	s_setprio 1
	s_add_u32 s58, s58, 0x100
	s_addc_u32 s59, s59, 0
	s_add_u32 s96, s96, 0x100
	s_addc_u32 s97, s97, 0
	s_cmp_ge_i32 s68, s78
	s_barrier
	s_cbranch_scc1 .LBB0_667

.LBB0_766:
	ds_read_b128 v[128:131], v215
	ds_read_b128 v[132:135], v215 offset:1024
	ds_read_b128 v[136:139], v215 offset:2048
	ds_read_b128 v[140:143], v215 offset:3072
	s_add_i32 s62, s24, 2
	s_add_u32 s26, s0, 0x80
	s_addc_u32 s25, s1, 0
	s_cmp_eq_u32 s51, s24
	s_cselect_b32 s24, s20, s26
	s_cselect_b32 s25, s21, s25
	s_cselect_b32 s27, s7, s61
	s_cselect_b32 s26, s6, s60
	v_lshl_add_u64 v[194:195], s[0:1], 0, v[186:187]
	s_add_i32 m0, s41, 0xc000
	ds_read_b128 v[144:147], v216
	ds_read_b128 v[148:151], v216 offset:1024
	ds_read_b128 v[152:155], v216 offset:2048
	ds_read_b128 v[156:159], v216 offset:3072
	ds_read_b128 v[160:163], v216 offset:4096
	ds_read_b128 v[164:167], v216 offset:5120
	ds_read_b128 v[168:171], v216 offset:6144
	ds_read_b128 v[172:175], v216 offset:7168
	global_load_lds_dwordx4 v[194:195], off
	v_lshl_add_u64 v[194:195], s[0:1], 0, v[188:189]
	s_add_i32 m0, s41, 0xe000
	s_nop 0
	global_load_lds_dwordx4 v[194:195], off
	s_waitcnt lgkmcnt(8)
	s_barrier
	s_waitcnt lgkmcnt(0)
	s_setprio 0
	s_waitcnt lgkmcnt(0)
	v_mfma_f32_16x16x32_bf16 v[124:127], v[128:131], v[144:147], v[124:127]
	v_mfma_f32_16x16x32_bf16 v[120:123], v[136:139], v[144:147], v[120:123]
	v_mfma_f32_16x16x32_bf16 v[108:111], v[128:131], v[152:155], v[108:111]
	v_mfma_f32_16x16x32_bf16 v[104:107], v[136:139], v[152:155], v[104:107]
	v_mfma_f32_16x16x32_bf16 v[92:95], v[128:131], v[160:163], v[92:95]
	v_mfma_f32_16x16x32_bf16 v[88:91], v[136:139], v[160:163], v[88:91]
	v_mfma_f32_16x16x32_bf16 v[76:79], v[128:131], v[168:171], v[76:79]
	v_mfma_f32_16x16x32_bf16 v[72:75], v[136:139], v[168:171], v[72:75]
	v_mfma_f32_16x16x32_bf16 v[124:127], v[132:135], v[148:151], v[124:127]
	v_mfma_f32_16x16x32_bf16 v[120:123], v[140:143], v[148:151], v[120:123]
	v_mfma_f32_16x16x32_bf16 v[108:111], v[132:135], v[156:159], v[108:111]
	v_mfma_f32_16x16x32_bf16 v[104:107], v[140:143], v[156:159], v[104:107]
	v_mfma_f32_16x16x32_bf16 v[92:95], v[132:135], v[164:167], v[92:95]
	v_mfma_f32_16x16x32_bf16 v[88:91], v[140:143], v[164:167], v[88:91]
	v_mfma_f32_16x16x32_bf16 v[76:79], v[132:135], v[172:175], v[76:79]
	v_mfma_f32_16x16x32_bf16 v[72:75], v[140:143], v[172:175], v[72:75]
	s_setprio 1
	s_barrier
	s_add_i32 s63, s55, s40
	v_lshl_add_u64 v[210:211], s[26:27], 0, v[178:179]
	s_mov_b32 m0, s63
	ds_read_b128 v[194:197], v217
	ds_read_b128 v[198:201], v217 offset:1024
	ds_read_b128 v[202:205], v217 offset:2048
	ds_read_b128 v[206:209], v217 offset:3072
	global_load_lds_dwordx4 v[210:211], off
	v_lshl_add_u64 v[218:219], s[26:27], 0, v[184:185]
	s_add_i32 m0, s63, 0x2000
	s_nop 0
	global_load_lds_dwordx4 v[218:219], off
	s_barrier
	s_waitcnt lgkmcnt(0)
	s_setprio 0
	s_waitcnt lgkmcnt(0)
	v_mfma_f32_16x16x32_bf16 v[116:119], v[194:197], v[144:147], v[116:119]
	v_mfma_f32_16x16x32_bf16 v[112:115], v[202:205], v[144:147], v[112:115]
	v_mfma_f32_16x16x32_bf16 v[100:103], v[194:197], v[152:155], v[100:103]
	v_mfma_f32_16x16x32_bf16 v[96:99], v[202:205], v[152:155], v[96:99]
	v_mfma_f32_16x16x32_bf16 v[84:87], v[194:197], v[160:163], v[84:87]
	v_mfma_f32_16x16x32_bf16 v[80:83], v[202:205], v[160:163], v[80:83]
	v_mfma_f32_16x16x32_bf16 v[68:71], v[194:197], v[168:171], v[68:71]
	v_mfma_f32_16x16x32_bf16 v[64:67], v[202:205], v[168:171], v[64:67]
	v_mfma_f32_16x16x32_bf16 v[116:119], v[198:201], v[148:151], v[116:119]
	v_mfma_f32_16x16x32_bf16 v[112:115], v[206:209], v[148:151], v[112:115]
	v_mfma_f32_16x16x32_bf16 v[100:103], v[198:201], v[156:159], v[100:103]
	v_mfma_f32_16x16x32_bf16 v[96:99], v[206:209], v[156:159], v[96:99]
	v_mfma_f32_16x16x32_bf16 v[84:87], v[198:201], v[164:167], v[84:87]
	v_mfma_f32_16x16x32_bf16 v[80:83], v[206:209], v[164:167], v[80:83]
	v_mfma_f32_16x16x32_bf16 v[68:71], v[198:201], v[172:175], v[68:71]
	v_mfma_f32_16x16x32_bf16 v[64:67], v[206:209], v[172:175], v[64:67]
	s_setprio 1
	s_mov_b32 m0, s41
	v_lshl_add_u64 v[220:221], s[24:25], 0, v[176:177]
	s_barrier
	ds_read_b128 v[144:147], v216 offset:16384
	ds_read_b128 v[148:151], v216 offset:17408
	ds_read_b128 v[152:155], v216 offset:18432
	ds_read_b128 v[156:159], v216 offset:19456
	ds_read_b128 v[160:163], v216 offset:20480
	ds_read_b128 v[164:167], v216 offset:21504
	ds_read_b128 v[168:171], v216 offset:22528
	ds_read_b128 v[172:175], v216 offset:23552
	global_load_lds_dwordx4 v[220:221], off
	v_lshl_add_u64 v[222:223], s[24:25], 0, v[182:183]
	s_mov_b32 m0, s42
	s_nop 0
	global_load_lds_dwordx4 v[222:223], off
	s_barrier
	s_waitcnt lgkmcnt(0)
	s_setprio 0
	s_waitcnt lgkmcnt(0)
	v_mfma_f32_16x16x32_bf16 v[60:63], v[128:131], v[144:147], v[60:63]
	v_mfma_f32_16x16x32_bf16 v[56:59], v[136:139], v[144:147], v[56:59]
	v_mfma_f32_16x16x32_bf16 v[44:47], v[128:131], v[152:155], v[44:47]
	v_mfma_f32_16x16x32_bf16 v[40:43], v[136:139], v[152:155], v[40:43]
	v_mfma_f32_16x16x32_bf16 v[28:31], v[128:131], v[160:163], v[28:31]
	v_mfma_f32_16x16x32_bf16 v[24:27], v[136:139], v[160:163], v[24:27]
	v_mfma_f32_16x16x32_bf16 v[12:15], v[128:131], v[168:171], v[12:15]
	v_mfma_f32_16x16x32_bf16 v[8:11], v[136:139], v[168:171], v[8:11]
	v_mfma_f32_16x16x32_bf16 v[60:63], v[132:135], v[148:151], v[60:63]
	v_mfma_f32_16x16x32_bf16 v[56:59], v[140:143], v[148:151], v[56:59]
	v_mfma_f32_16x16x32_bf16 v[44:47], v[132:135], v[156:159], v[44:47]
	v_mfma_f32_16x16x32_bf16 v[40:43], v[140:143], v[156:159], v[40:43]
	v_mfma_f32_16x16x32_bf16 v[28:31], v[132:135], v[164:167], v[28:31]
	v_mfma_f32_16x16x32_bf16 v[24:27], v[140:143], v[164:167], v[24:27]
	v_mfma_f32_16x16x32_bf16 v[12:15], v[132:135], v[172:175], v[12:15]
	v_mfma_f32_16x16x32_bf16 v[8:11], v[140:143], v[172:175], v[8:11]
	s_setprio 1
	s_barrier
	s_add_u32 s26, s26, s8
	s_addc_u32 s27, s27, s9
	s_add_i32 s63, s56, s40
	v_lshl_add_u64 v[224:225], s[26:27], 0, v[178:179]
	s_mov_b32 m0, s63
	v_lshl_add_u64 v[226:227], s[26:27], 0, v[184:185]
	global_load_lds_dwordx4 v[224:225], off
	s_add_i32 m0, s63, 0x2000
	s_nop 0
	global_load_lds_dwordx4 v[226:227], off
	s_waitcnt vmcnt(6)
	s_barrier
	s_setprio 0
	v_mfma_f32_16x16x32_bf16 v[52:55], v[194:197], v[144:147], v[52:55]
	v_mfma_f32_16x16x32_bf16 v[48:51], v[202:205], v[144:147], v[48:51]
	v_mfma_f32_16x16x32_bf16 v[36:39], v[194:197], v[152:155], v[36:39]
	v_mfma_f32_16x16x32_bf16 v[32:35], v[202:205], v[152:155], v[32:35]
	v_mfma_f32_16x16x32_bf16 v[20:23], v[194:197], v[160:163], v[20:23]
	v_mfma_f32_16x16x32_bf16 v[16:19], v[202:205], v[160:163], v[16:19]
	v_mfma_f32_16x16x32_bf16 v[4:7], v[194:197], v[168:171], v[4:7]
	v_mfma_f32_16x16x32_bf16 v[0:3], v[202:205], v[168:171], v[0:3]
	v_mfma_f32_16x16x32_bf16 v[52:55], v[198:201], v[148:151], v[52:55]
	v_mfma_f32_16x16x32_bf16 v[48:51], v[206:209], v[148:151], v[48:51]
	v_mfma_f32_16x16x32_bf16 v[36:39], v[198:201], v[156:159], v[36:39]
	v_mfma_f32_16x16x32_bf16 v[32:35], v[206:209], v[156:159], v[32:35]
	v_mfma_f32_16x16x32_bf16 v[20:23], v[198:201], v[164:167], v[20:23]
	v_mfma_f32_16x16x32_bf16 v[16:19], v[206:209], v[164:167], v[16:19]
	v_mfma_f32_16x16x32_bf16 v[4:7], v[198:201], v[172:175], v[4:7]
	v_mfma_f32_16x16x32_bf16 v[0:3], v[206:209], v[172:175], v[0:3]
	s_setprio 1
	s_add_i32 s26, 0, 0x18000
	v_add_u32_e32 v140, s26, v214
	s_barrier
	ds_read_b128 v[128:131], v140
	ds_read_b128 v[132:135], v140 offset:1024
	ds_read_b128 v[136:139], v140 offset:2048
	ds_read_b128 v[140:143], v140 offset:3072
	s_add_u32 s24, s24, s8
	s_addc_u32 s25, s25, s9
	s_mov_b32 m0, s43
	v_lshl_add_u64 v[194:195], s[24:25], 0, v[176:177]
	ds_read_b128 v[144:147], v216 offset:32768
	ds_read_b128 v[148:151], v216 offset:33792
	ds_read_b128 v[152:155], v216 offset:34816
	ds_read_b128 v[156:159], v216 offset:35840
	ds_read_b128 v[160:163], v216 offset:36864
	ds_read_b128 v[164:167], v216 offset:37888
	ds_read_b128 v[168:171], v216 offset:38912
	ds_read_b128 v[172:175], v216 offset:39936
	global_load_lds_dwordx4 v[194:195], off
	v_lshl_add_u64 v[194:195], s[24:25], 0, v[182:183]
	s_mov_b32 m0, s44
	s_nop 0
	global_load_lds_dwordx4 v[194:195], off
	s_waitcnt lgkmcnt(8)
	s_barrier
	s_waitcnt lgkmcnt(0)
	s_setprio 0
	s_waitcnt lgkmcnt(0)
	v_mfma_f32_16x16x32_bf16 v[124:127], v[128:131], v[144:147], v[124:127]
	v_mfma_f32_16x16x32_bf16 v[120:123], v[136:139], v[144:147], v[120:123]
	v_mfma_f32_16x16x32_bf16 v[108:111], v[128:131], v[152:155], v[108:111]
	v_mfma_f32_16x16x32_bf16 v[104:107], v[136:139], v[152:155], v[104:107]
	v_mfma_f32_16x16x32_bf16 v[92:95], v[128:131], v[160:163], v[92:95]
	v_mfma_f32_16x16x32_bf16 v[88:91], v[136:139], v[160:163], v[88:91]
	v_mfma_f32_16x16x32_bf16 v[76:79], v[128:131], v[168:171], v[76:79]
	v_mfma_f32_16x16x32_bf16 v[72:75], v[136:139], v[168:171], v[72:75]
	v_mfma_f32_16x16x32_bf16 v[124:127], v[132:135], v[148:151], v[124:127]
	v_mfma_f32_16x16x32_bf16 v[120:123], v[140:143], v[148:151], v[120:123]
	v_mfma_f32_16x16x32_bf16 v[108:111], v[132:135], v[156:159], v[108:111]
	v_mfma_f32_16x16x32_bf16 v[104:107], v[140:143], v[156:159], v[104:107]
	v_mfma_f32_16x16x32_bf16 v[92:95], v[132:135], v[164:167], v[92:95]
	v_mfma_f32_16x16x32_bf16 v[88:91], v[140:143], v[164:167], v[88:91]
	v_mfma_f32_16x16x32_bf16 v[76:79], v[132:135], v[172:175], v[76:79]
	v_mfma_f32_16x16x32_bf16 v[72:75], v[140:143], v[172:175], v[72:75]
	s_setprio 1
	s_barrier
	s_add_i32 s24, 0, 0x1c000
	s_add_i32 s25, s26, s40
	v_add_u32_e32 v206, s24, v214
	v_lshl_add_u64 v[210:211], v[210:211], 0, s[12:13]
	s_mov_b32 m0, s25
	ds_read_b128 v[194:197], v206
	ds_read_b128 v[198:201], v206 offset:1024
	ds_read_b128 v[202:205], v206 offset:2048
	ds_read_b128 v[206:209], v206 offset:3072
	global_load_lds_dwordx4 v[210:211], off
	v_lshl_add_u64 v[210:211], v[218:219], 0, s[12:13]
	s_add_i32 m0, s25, 0x2000
	s_nop 0
	global_load_lds_dwordx4 v[210:211], off
	s_barrier
	s_waitcnt lgkmcnt(0)
	s_setprio 0
	s_waitcnt lgkmcnt(0)
	v_mfma_f32_16x16x32_bf16 v[116:119], v[194:197], v[144:147], v[116:119]
	v_mfma_f32_16x16x32_bf16 v[112:115], v[202:205], v[144:147], v[112:115]
	v_mfma_f32_16x16x32_bf16 v[100:103], v[194:197], v[152:155], v[100:103]
	v_mfma_f32_16x16x32_bf16 v[96:99], v[202:205], v[152:155], v[96:99]
	v_mfma_f32_16x16x32_bf16 v[84:87], v[194:197], v[160:163], v[84:87]
	v_mfma_f32_16x16x32_bf16 v[80:83], v[202:205], v[160:163], v[80:83]
	v_mfma_f32_16x16x32_bf16 v[68:71], v[194:197], v[168:171], v[68:71]
	v_mfma_f32_16x16x32_bf16 v[64:67], v[202:205], v[168:171], v[64:67]
	v_mfma_f32_16x16x32_bf16 v[116:119], v[198:201], v[148:151], v[116:119]
	v_mfma_f32_16x16x32_bf16 v[112:115], v[206:209], v[148:151], v[112:115]
	v_mfma_f32_16x16x32_bf16 v[100:103], v[198:201], v[156:159], v[100:103]
	v_mfma_f32_16x16x32_bf16 v[96:99], v[206:209], v[156:159], v[96:99]
	v_mfma_f32_16x16x32_bf16 v[84:87], v[198:201], v[164:167], v[84:87]
	v_mfma_f32_16x16x32_bf16 v[80:83], v[206:209], v[164:167], v[80:83]
	v_mfma_f32_16x16x32_bf16 v[68:71], v[198:201], v[172:175], v[68:71]
	v_mfma_f32_16x16x32_bf16 v[64:67], v[206:209], v[172:175], v[64:67]
	s_setprio 1
	s_mov_b32 m0, s46
	v_lshl_add_u64 v[210:211], v[220:221], 0, s[12:13]
	s_barrier
	ds_read_b128 v[144:147], v216 offset:49152
	ds_read_b128 v[148:151], v216 offset:50176
	ds_read_b128 v[152:155], v216 offset:51200
	ds_read_b128 v[156:159], v216 offset:52224
	ds_read_b128 v[160:163], v216 offset:53248
	ds_read_b128 v[164:167], v216 offset:54272
	ds_read_b128 v[168:171], v216 offset:55296
	ds_read_b128 v[172:175], v216 offset:56320
	global_load_lds_dwordx4 v[210:211], off
	v_lshl_add_u64 v[210:211], v[222:223], 0, s[12:13]
	s_mov_b32 m0, s47
	s_nop 0
	global_load_lds_dwordx4 v[210:211], off
	s_barrier
	s_waitcnt lgkmcnt(0)
	s_setprio 0
	s_waitcnt lgkmcnt(0)
	v_mfma_f32_16x16x32_bf16 v[60:63], v[128:131], v[144:147], v[60:63]
	v_mfma_f32_16x16x32_bf16 v[56:59], v[136:139], v[144:147], v[56:59]
	v_mfma_f32_16x16x32_bf16 v[44:47], v[128:131], v[152:155], v[44:47]
	v_mfma_f32_16x16x32_bf16 v[40:43], v[136:139], v[152:155], v[40:43]
	v_mfma_f32_16x16x32_bf16 v[28:31], v[128:131], v[160:163], v[28:31]
	v_mfma_f32_16x16x32_bf16 v[24:27], v[136:139], v[160:163], v[24:27]
	v_mfma_f32_16x16x32_bf16 v[12:15], v[128:131], v[168:171], v[12:15]
	v_mfma_f32_16x16x32_bf16 v[8:11], v[136:139], v[168:171], v[8:11]
	v_mfma_f32_16x16x32_bf16 v[60:63], v[132:135], v[148:151], v[60:63]
	v_mfma_f32_16x16x32_bf16 v[56:59], v[140:143], v[148:151], v[56:59]
	v_mfma_f32_16x16x32_bf16 v[44:47], v[132:135], v[156:159], v[44:47]
	v_mfma_f32_16x16x32_bf16 v[40:43], v[140:143], v[156:159], v[40:43]
	v_mfma_f32_16x16x32_bf16 v[28:31], v[132:135], v[164:167], v[28:31]
	v_mfma_f32_16x16x32_bf16 v[24:27], v[140:143], v[164:167], v[24:27]
	v_mfma_f32_16x16x32_bf16 v[12:15], v[132:135], v[172:175], v[12:15]
	v_mfma_f32_16x16x32_bf16 v[8:11], v[140:143], v[172:175], v[8:11]
	s_setprio 1
	s_barrier
	s_add_i32 s24, s24, s40
	v_lshl_add_u64 v[128:129], v[224:225], 0, s[12:13]
	s_mov_b32 m0, s24
	s_nop 0
	global_load_lds_dwordx4 v[128:129], off
	v_lshl_add_u64 v[128:129], v[226:227], 0, s[12:13]
	s_add_i32 m0, s24, 0x2000
	s_nop 0
	global_load_lds_dwordx4 v[128:129], off
	s_waitcnt vmcnt(6)
	s_barrier
	s_setprio 0
	v_mfma_f32_16x16x32_bf16 v[52:55], v[194:197], v[144:147], v[52:55]
	v_mfma_f32_16x16x32_bf16 v[48:51], v[202:205], v[144:147], v[48:51]
	v_mfma_f32_16x16x32_bf16 v[36:39], v[194:197], v[152:155], v[36:39]
	v_mfma_f32_16x16x32_bf16 v[32:35], v[202:205], v[152:155], v[32:35]
	v_mfma_f32_16x16x32_bf16 v[20:23], v[194:197], v[160:163], v[20:23]
	v_mfma_f32_16x16x32_bf16 v[16:19], v[202:205], v[160:163], v[16:19]
	v_mfma_f32_16x16x32_bf16 v[4:7], v[194:197], v[168:171], v[4:7]
	v_mfma_f32_16x16x32_bf16 v[0:3], v[202:205], v[168:171], v[0:3]
	v_mfma_f32_16x16x32_bf16 v[52:55], v[198:201], v[148:151], v[52:55]
	v_mfma_f32_16x16x32_bf16 v[48:51], v[206:209], v[148:151], v[48:51]
	v_mfma_f32_16x16x32_bf16 v[36:39], v[198:201], v[156:159], v[36:39]
	v_mfma_f32_16x16x32_bf16 v[32:35], v[206:209], v[156:159], v[32:35]
	v_mfma_f32_16x16x32_bf16 v[20:23], v[198:201], v[164:167], v[20:23]
	v_mfma_f32_16x16x32_bf16 v[16:19], v[206:209], v[164:167], v[16:19]
	v_mfma_f32_16x16x32_bf16 v[4:7], v[198:201], v[172:175], v[4:7]
	v_mfma_f32_16x16x32_bf16 v[0:3], v[206:209], v[172:175], v[0:3]
	s_setprio 1
	s_add_u32 s0, s0, 0x100
	s_addc_u32 s1, s1, 0
	s_add_u32 s60, s60, 0x100
	s_addc_u32 s61, s61, 0
	s_cmp_ge_i32 s62, s48
	s_mov_b32 s24, s62
	s_barrier
	s_cbranch_scc0 .LBB0_766
